# barrier with early L1 invalidate; spin caps restored to the original 1<<18 polls
# baseline (speedup 1.0000x reference)
.Lxb_ipoll_1:
	global_load_dword v13, v3, s[100:101] sc1
	s_waitcnt vmcnt(0) lgkmcnt(0)
	v_cmp_eq_u32_e32 vcc, v13, v14
	s_cbranch_vccnz .Lxb_iok_1
	s_sleep 1
	v_add_u32_e32 v16, 1, v16
	v_cmp_gt_u32_e32 vcc, 0x40000, v16
	s_cbranch_vccnz .Lxb_ipoll_1
